# SSD: flag prefetch load back before barrier D with a conditional counted staging wait (vmcnt(1) when the flag load is in flight); norm2 prologue loads batched; kscale loads batched in H conv_mixer
# speedup vs baseline: 1.0103x; 1.0034x over previous
.LBB0_1010:
	s_cmp_gt_u32 s47, 1
	s_cselect_b32 s22, 35, 1
	s_sub_i32 s55, s22, s47
	s_cmp_eq_u32 s47, 0
	s_cselect_b64 s[92:93], -1, 0
	s_cmp_lt_u32 s47, 18
	s_cselect_b64 s[22:23], -1, 0
	s_cmp_lt_u32 s47, 2
	v_cndmask_b32_e64 v57, 0, 1, s[22:23]
	s_cselect_b64 s[22:23], -1, 0
	v_cndmask_b32_e64 v56, 0, 1, s[92:93]
	s_and_b64 s[24:25], s[22:23], exec
	v_readfirstlane_b32 s24, v56
	v_readfirstlane_b32 s25, v57
	s_cselect_b32 s24, s24, s25
	s_and_b64 s[22:23], s[40:41], s[22:23]
	s_bitcmp1_b32 s24, 0
	s_cselect_b64 s[78:79], -1, 0
	s_or_b64 s[90:91], s[22:23], s[78:79]
	s_and_b64 vcc, exec, s[90:91]
	v_mov_b32_e32 v66, 1
	s_and_b64 s[100:101], s[90:91], exec
	s_cbranch_scc1 .Lmy_noflag_a
	s_lshl_b32 s100, s55, 5
	s_ashr_i32 s101, s100, 31
	s_add_u32 s100, s31, s100
	s_addc_u32 s101, s43, s101
	global_load_dword v66, v65, s[100:101] sc1
.Lmy_noflag_a:
.LBB0_1012:
	s_and_b32 s35, s47, 1
	s_lshl_b32 s24, s35, 10
	s_add_i32 s54, s24, 0
	s_add_i32 s54, s54, 0x22800
	v_lshlrev_b32_e32 v56, 2, v136
	s_waitcnt lgkmcnt(0)
	s_barrier
	s_waitcnt vmcnt(9)
	ds_write_b128 v152, v[0:3]
	s_waitcnt vmcnt(8)
	ds_write_b128 v152, v[4:7] offset:34816
	s_waitcnt vmcnt(7)
	ds_write_b128 v153, v[8:11]
	s_waitcnt vmcnt(6)
	ds_write_b128 v153, v[12:15] offset:34816
	s_waitcnt vmcnt(5)
	ds_write_b128 v154, v[16:19]
	s_waitcnt vmcnt(4)
	ds_write_b128 v154, v[20:23] offset:34816
	s_waitcnt vmcnt(3)
	ds_write_b128 v155, v[24:27]
	s_waitcnt vmcnt(2)
	ds_write_b128 v155, v[28:31] offset:34816
	s_and_b64 s[100:101], s[90:91], exec
	s_cbranch_scc1 .Lmy_w0_a
	s_waitcnt vmcnt(1)
	s_branch .Lmy_w1_a
.Lmy_w0_a:
	s_waitcnt vmcnt(0)
.Lmy_w1_a:
	ds_write2_b64 v156, v[36:37], v[38:39] offset1:4
	ds_write2_b64 v156, v[32:33], v[34:35] offset0:8 offset1:12
	v_mov_b32_e32 v57, s54
	v_add_u32_e32 v58, s54, v56
	ds_read_b32 v57, v57
	ds_read_b32 v58, v58
	s_lshl_b32 s27, s35, 9
	s_add_i32 s34, s27, 0
	s_add_i32 s34, s34, 0x23000
	v_add_u32_e32 v56, s34, v56
	s_waitcnt lgkmcnt(0)
	v_sub_f32_e32 v57, v57, v58
	ds_read_b32 v56, v56
	v_mul_f32_e32 v57, 0x3fb8aa3b, v57
	v_exp_f32_e32 v57, v57
	v_lshlrev_b32_e32 v58, 16, v36
	v_and_b32_e32 v59, 0xffff0000, v36
	v_lshlrev_b32_e32 v60, 16, v37
	s_waitcnt lgkmcnt(0)
	v_mul_f32_e32 v56, v56, v57
	v_and_b32_e32 v61, 0xffff0000, v37
	v_pk_mul_f32 v[58:59], v[56:57], v[58:59] op_sel_hi:[0,1]
	v_pk_mul_f32 v[60:61], v[56:57], v[60:61] op_sel_hi:[0,1]
	v_cvt_pk_bf16_f32 v58, v58, v59
	v_cvt_pk_bf16_f32 v59, v60, v61
	v_lshlrev_b32_e32 v60, 16, v38
	v_and_b32_e32 v61, 0xffff0000, v38
	v_lshlrev_b32_e32 v62, 16, v39
	v_and_b32_e32 v63, 0xffff0000, v39
	v_pk_mul_f32 v[60:61], v[56:57], v[60:61] op_sel_hi:[0,1]
	v_pk_mul_f32 v[62:63], v[56:57], v[62:63] op_sel_hi:[0,1]
	v_cvt_pk_bf16_f32 v60, v60, v61
	v_cvt_pk_bf16_f32 v61, v62, v63
	ds_write2_b64 v157, v[58:59], v[60:61] offset1:4
	v_lshlrev_b32_e32 v58, 16, v32
	v_and_b32_e32 v59, 0xffff0000, v32
	v_lshlrev_b32_e32 v60, 16, v33
	v_and_b32_e32 v61, 0xffff0000, v33
	v_pk_mul_f32 v[58:59], v[56:57], v[58:59] op_sel_hi:[0,1]
	v_pk_mul_f32 v[60:61], v[56:57], v[60:61] op_sel_hi:[0,1]
	v_cvt_pk_bf16_f32 v58, v58, v59
	v_cvt_pk_bf16_f32 v59, v60, v61
	v_lshlrev_b32_e32 v60, 16, v34
	v_and_b32_e32 v61, 0xffff0000, v34
	v_lshlrev_b32_e32 v62, 16, v35
	v_and_b32_e32 v63, 0xffff0000, v35
	s_cmp_lg_u32 s47, 33
	v_pk_mul_f32 v[60:61], v[56:57], v[60:61] op_sel_hi:[0,1]
	v_pk_mul_f32 v[56:57], v[56:57], v[62:63] op_sel_hi:[0,1]
	s_cselect_b64 s[62:63], -1, 0
	v_cvt_pk_bf16_f32 v60, v60, v61
	v_cvt_pk_bf16_f32 v61, v56, v57
	s_and_b64 s[38:39], s[2:3], s[62:63]
	ds_write2_b64 v157, v[58:59], v[60:61] offset0:8 offset1:12
	s_and_saveexec_b64 s[24:25], s[38:39]
	s_xor_b32 s27, s27, 0x200
	v_add_u32_e32 v56, s27, v144
	ds_write_b32 v56, v142
	s_or_b64 exec, exec, s[24:25]
	s_cmp_lt_i32 s26, 0
	s_cbranch_scc1 .LBB0_1018
	s_waitcnt vmcnt(0)
	s_and_saveexec_b64 s[24:25], s[4:5]
	s_cbranch_execz .LBB0_1017
	s_lshl_b32 s66, s26, 3
	s_lshl_b64 s[26:27], s[66:67], 2
	s_add_u32 s26, s31, s26
	s_addc_u32 s27, s43, s27
	v_mov_b32_e32 v56, 1
	global_store_dword v65, v56, s[26:27] sc1

.LBB0_1132:
	s_cmp_eq_u32 s34, 0
	s_cselect_b64 s[56:57], -1, 0
	s_cmp_lt_u32 s34, 18
	s_cselect_b64 s[20:21], -1, 0
	s_cmp_lt_u32 s34, 2
	s_cselect_b64 s[62:63], -1, 0
	v_cndmask_b32_e64 v56, 0, 1, s[56:57]
	v_cndmask_b32_e64 v57, 0, 1, s[20:21]
	s_and_b64 s[20:21], s[62:63], exec
	v_readfirstlane_b32 s20, v56
	v_readfirstlane_b32 s21, v57
	s_cselect_b32 s20, s20, s21
	s_and_b64 s[22:23], s[40:41], s[62:63]
	s_bitcmp1_b32 s20, 0
	s_cselect_b64 s[36:37], -1, 0
	s_or_b64 s[90:91], s[22:23], s[36:37]
	s_and_b64 vcc, exec, s[90:91]
	v_mov_b32_e32 v66, 1
	s_and_b64 s[100:101], s[90:91], exec
	s_cbranch_scc1 .Lmy_noflag_b
	s_lshl_b32 s100, s34, 5
	s_add_u32 s100, s47, s100
	s_addc_u32 s101, s51, 0
	global_load_dword v66, v65, s[100:101] sc1
.Lmy_noflag_b:
.LBB0_1134:
	s_and_b32 s83, s34, 1
	s_lshl_b32 s20, s83, 10
	s_add_i32 s35, s20, 0
	s_add_i32 s35, s35, 0x22800
	v_lshlrev_b32_e32 v56, 2, v138
	s_waitcnt lgkmcnt(0)
	s_barrier
	s_waitcnt vmcnt(9)
	ds_write_b128 v155, v[0:3]
	s_waitcnt vmcnt(8)
	ds_write_b128 v155, v[4:7] offset:34816
	s_waitcnt vmcnt(7)
	ds_write_b128 v156, v[8:11]
	s_waitcnt vmcnt(6)
	ds_write_b128 v156, v[12:15] offset:34816
	s_waitcnt vmcnt(5)
	ds_write_b128 v157, v[16:19]
	s_waitcnt vmcnt(4)
	ds_write_b128 v157, v[20:23] offset:34816
	s_waitcnt vmcnt(3)
	ds_write_b128 v158, v[24:27]
	s_waitcnt vmcnt(2)
	ds_write_b128 v158, v[28:31] offset:34816
	s_and_b64 s[100:101], s[90:91], exec
	s_cbranch_scc1 .Lmy_w0_b
	s_waitcnt vmcnt(1)
	s_branch .Lmy_w1_b
.Lmy_w0_b:
	s_waitcnt vmcnt(0)
.Lmy_w1_b:
	ds_write2_b64 v159, v[36:37], v[38:39] offset1:4
	ds_write2_b64 v159, v[32:33], v[34:35] offset0:8 offset1:12
	v_mov_b32_e32 v57, s35
	v_add_u32_e32 v58, s35, v56
	ds_read_b32 v57, v57 offset:508
	ds_read_b32 v58, v58
	s_lshl_b32 s26, s83, 9
	s_add_i32 s77, s26, 0
	s_add_i32 s77, s77, 0x23000
	v_add_u32_e32 v56, s77, v56
	s_waitcnt lgkmcnt(0)
	v_sub_f32_e32 v57, v57, v58
	ds_read_b32 v56, v56
	v_mul_f32_e32 v57, 0x3fb8aa3b, v57
	v_exp_f32_e32 v57, v57
	v_lshlrev_b32_e32 v58, 16, v36
	v_and_b32_e32 v59, 0xffff0000, v36
	v_lshlrev_b32_e32 v60, 16, v37
	s_waitcnt lgkmcnt(0)
	v_mul_f32_e32 v56, v56, v57
	v_and_b32_e32 v61, 0xffff0000, v37
	v_pk_mul_f32 v[58:59], v[56:57], v[58:59] op_sel_hi:[0,1]
	v_pk_mul_f32 v[60:61], v[56:57], v[60:61] op_sel_hi:[0,1]
	v_cvt_pk_bf16_f32 v58, v58, v59
	v_cvt_pk_bf16_f32 v59, v60, v61
	v_lshlrev_b32_e32 v60, 16, v38
	v_and_b32_e32 v61, 0xffff0000, v38
	v_lshlrev_b32_e32 v62, 16, v39
	v_and_b32_e32 v63, 0xffff0000, v39
	v_pk_mul_f32 v[60:61], v[56:57], v[60:61] op_sel_hi:[0,1]
	v_pk_mul_f32 v[62:63], v[56:57], v[62:63] op_sel_hi:[0,1]
	v_cvt_pk_bf16_f32 v60, v60, v61
	v_cvt_pk_bf16_f32 v61, v62, v63
	ds_write2_b64 v160, v[58:59], v[60:61] offset1:4
	v_lshlrev_b32_e32 v58, 16, v32
	v_and_b32_e32 v59, 0xffff0000, v32
	v_lshlrev_b32_e32 v60, 16, v33
	v_and_b32_e32 v61, 0xffff0000, v33
	v_pk_mul_f32 v[58:59], v[56:57], v[58:59] op_sel_hi:[0,1]
	v_pk_mul_f32 v[60:61], v[56:57], v[60:61] op_sel_hi:[0,1]
	v_cvt_pk_bf16_f32 v58, v58, v59
	v_cvt_pk_bf16_f32 v59, v60, v61
	v_lshlrev_b32_e32 v60, 16, v34
	v_and_b32_e32 v61, 0xffff0000, v34
	v_lshlrev_b32_e32 v62, 16, v35
	v_and_b32_e32 v63, 0xffff0000, v35
	s_cmp_lg_u32 s34, 33
	v_pk_mul_f32 v[60:61], v[56:57], v[60:61] op_sel_hi:[0,1]
	v_pk_mul_f32 v[56:57], v[56:57], v[62:63] op_sel_hi:[0,1]
	s_cselect_b64 s[20:21], -1, 0
	v_cvt_pk_bf16_f32 v60, v60, v61
	v_cvt_pk_bf16_f32 v61, v56, v57
	s_and_b64 s[38:39], s[2:3], s[20:21]
	ds_write2_b64 v160, v[58:59], v[60:61] offset0:8 offset1:12
	s_and_saveexec_b64 s[24:25], s[38:39]
	s_xor_b32 s26, s26, 0x200
	v_add_u32_e32 v56, s26, v145
	ds_write_b32 v56, v144
	s_or_b64 exec, exec, s[24:25]
	s_cmp_lt_i32 s27, 0
	s_cbranch_scc1 .LBB0_1140
	s_waitcnt vmcnt(0)
	s_and_saveexec_b64 s[24:25], s[4:5]
	s_cbranch_execz .LBB0_1139
	s_lshl_b32 s66, s27, 3
	s_lshl_b64 s[26:27], s[66:67], 2
	s_add_u32 s26, s47, s26
	s_addc_u32 s27, s51, s27
	v_mov_b32_e32 v56, 1
	global_store_dword v65, v56, s[26:27] sc1

.LBB0_2097:
	s_andn2_saveexec_b64 s[12:13], s[12:13]
	s_cbranch_execz .LBB0_2099
	v_ashrrev_i32_e32 v97, 31, v96
	v_lshlrev_b64 v[0:1], 12, v[96:97]
	v_lshl_add_u64 v[0:1], v[88:89], 0, v[0:1]
	global_load_dwordx2 v[18:19], v[0:1], off
	global_load_dwordx2 v[22:23], v[0:1], off offset:512
	global_load_dwordx2 v[26:27], v[0:1], off offset:1024
	global_load_dwordx2 v[30:31], v[0:1], off offset:1536
	s_waitcnt vmcnt(3)
	v_lshlrev_b32_e32 v16, 16, v18
	v_and_b32_e32 v17, 0xffff0000, v18
	v_lshlrev_b32_e32 v18, 16, v19
	v_and_b32_e32 v19, 0xffff0000, v19
	s_waitcnt vmcnt(2)
	v_lshlrev_b32_e32 v20, 16, v22
	v_and_b32_e32 v21, 0xffff0000, v22
	v_lshlrev_b32_e32 v22, 16, v23
	v_and_b32_e32 v23, 0xffff0000, v23
	s_waitcnt vmcnt(1)
	v_lshlrev_b32_e32 v24, 16, v26
	v_and_b32_e32 v25, 0xffff0000, v26
	v_lshlrev_b32_e32 v26, 16, v27
	v_and_b32_e32 v27, 0xffff0000, v27
	s_waitcnt vmcnt(0)
	v_lshlrev_b32_e32 v28, 16, v30
	v_and_b32_e32 v29, 0xffff0000, v30
	v_lshlrev_b32_e32 v30, 16, v31
	v_and_b32_e32 v31, 0xffff0000, v31

.LBB0_2325:
	s_cmp_eq_u64 s[28:29], 0
	v_add_u32_e32 v125, 0x420, v117
	v_add_u32_e32 v124, 0x428, v117
	v_add_u32_e32 v123, 0x840, v117
	v_add_u32_e32 v121, 0x848, v117
	v_add_u32_e32 v122, 0xc60, v117
	v_add_u32_e32 v120, 0xc68, v117
	v_add_u32_e32 v119, 0x1080, v117
	v_add_u32_e32 v64, 0x1088, v117
	v_add_u32_e32 v118, 0x14a0, v117
	s_cbranch_scc1 .LBB0_2354
	v_ashrrev_i32_e32 v101, 31, v100
	v_lshl_add_u64 v[66:67], v[100:101], 2, s[28:29]
	global_load_dword v130, v[66:67], off
	s_ashr_i32 s21, s20, 31
	v_lshl_add_u64 v[66:67], s[20:21], 0, v[104:105]
	v_lshl_add_u64 v[100:101], v[66:67], 2, s[28:29]
	global_load_dword v132, v[100:101], off offset:32
	global_load_dword v134, v[100:101], off offset:64
	global_load_dword v136, v[100:101], off offset:96
	global_load_dword v138, v[100:101], off offset:128
	global_load_dword v140, v[100:101], off offset:160
	global_load_dword v142, v[100:101], off offset:192
	global_load_dword v144, v[100:101], off offset:224
	s_waitcnt vmcnt(7)
	v_pk_mul_f32 v[100:101], v[70:71], v[130:131] op_sel_hi:[1,0]
	v_pk_mul_f32 v[66:67], v[68:69], v[130:131] op_sel_hi:[1,0]
	ds_write2_b32 v117, v66, v67 offset1:1
	ds_write2_b32 v117, v100, v101 offset0:2 offset1:3
	s_waitcnt vmcnt(6)
	v_pk_mul_f32 v[102:103], v[74:75], v[132:133] op_sel_hi:[1,0]
	v_pk_mul_f32 v[66:67], v[72:73], v[132:133] op_sel_hi:[1,0]
	ds_write2_b32 v125, v66, v67 offset1:1
	ds_write2_b32 v124, v102, v103 offset1:1
	s_waitcnt vmcnt(5)
	v_pk_mul_f32 v[102:103], v[78:79], v[134:135] op_sel_hi:[1,0]
	v_pk_mul_f32 v[66:67], v[76:77], v[134:135] op_sel_hi:[1,0]
	ds_write2_b32 v123, v66, v67 offset1:1
	ds_write2_b32 v121, v102, v103 offset1:1
	s_waitcnt vmcnt(4)
	v_pk_mul_f32 v[102:103], v[82:83], v[136:137] op_sel_hi:[1,0]
	v_pk_mul_f32 v[66:67], v[80:81], v[136:137] op_sel_hi:[1,0]
	ds_write2_b32 v122, v66, v67 offset1:1
	ds_write2_b32 v120, v102, v103 offset1:1
	s_waitcnt vmcnt(3)
	v_pk_mul_f32 v[102:103], v[90:91], v[138:139] op_sel_hi:[1,0]
	v_pk_mul_f32 v[66:67], v[88:89], v[138:139] op_sel_hi:[1,0]
	ds_write2_b32 v119, v66, v67 offset1:1
	ds_write2_b32 v64, v102, v103 offset1:1
	s_waitcnt vmcnt(2)
	v_pk_mul_f32 v[66:67], v[86:87], v[140:141] op_sel_hi:[1,0]
	v_pk_mul_f32 v[102:103], v[84:85], v[140:141] op_sel_hi:[1,0]
	ds_write2_b32 v118, v102, v103 offset1:1
	ds_write_b32 v117, v66 offset:5288
	s_waitcnt vmcnt(1)
	v_pk_mul_f32 v[108:109], v[94:95], v[142:143] op_sel_hi:[1,0]
	v_pk_mul_f32 v[110:111], v[92:93], v[142:143] op_sel_hi:[1,0]
	s_waitcnt vmcnt(0)
	v_pk_mul_f32 v[102:103], v[98:99], v[144:145] op_sel_hi:[1,0]
	v_pk_mul_f32 v[100:101], v[96:97], v[144:145] op_sel_hi:[1,0]
	s_cbranch_execnz .LBB0_2328
